# G6 K-loop: B operand in a 3-slot LDS ring (two K-tiles of B in flight, counted vmcnt(4)), A second stage moved to LDS 0x22000 (static LDS +28656 B)
# speedup vs baseline: 1.0369x; 1.0182x over previous
.LBB0_219:
	s_mov_b64 s[74:75], 0
	s_add_u32 s66, s56, s74
	v_readlane_b32 s4, v250, 1
	s_addc_u32 s67, s57, s75
	s_lshl_b64 s[30:31], s[74:75], 2
	v_readlane_b32 s6, v250, 3
	v_readlane_b32 s7, v250, 4
	s_add_u32 s68, s6, s30
	s_addc_u32 s69, s7, s31
	s_cmp_lt_i32 s72, 6
	s_mov_b64 s[0:1], -1
	v_readlane_b32 s27, v254, 28
	v_readlane_b32 s5, v250, 2
	s_cbranch_scc1 .LBB0_794
	s_cmp_lt_i32 s72, 8
	s_cbranch_scc1 .LBB0_256
	s_cmp_gt_i32 s72, 8
	s_cbranch_scc0 .LBB0_238
	s_mov_b64 s[0:1], src_shared_base
	s_add_i32 s0, 0, 0x2100c
	s_cmp_lg_u32 s0, -1
	s_cselect_b32 s0, s0, 0
	s_cselect_b32 s4, s1, 0
	v_mov_b32_e32 v2, s0
	s_add_i32 s0, 0, 0x21008
	s_cmp_lg_u32 s0, -1
	v_mov_b32_e32 v0, v224
	v_mov_b32_e32 v3, s4
	s_cselect_b32 s0, s0, 0
	s_cselect_b32 s1, s1, 0
	flat_load_dword v1, v[2:3] sc0 sc1
	s_waitcnt vmcnt(0)
	v_mov_b32_e32 v2, s0
	v_mov_b32_e32 v3, s1
	flat_load_dword v147, v[2:3] sc0 sc1
	s_waitcnt vmcnt(0) lgkmcnt(0)
	v_cmp_gt_i32_e32 vcc, 32, v147
	s_and_saveexec_b64 s[36:37], vcc
	s_cbranch_execz .LBB0_237
	v_lshlrev_b32_e32 v166, 3, v1
	v_ashrrev_i32_e32 v1, 31, v147
	v_lshrrev_b32_e32 v1, 30, v1
	v_add_u32_e32 v1, v147, v1
	v_lshrrev_b32_e32 v2, 2, v1
	v_and_b32_e32 v1, 0xfffffc, v1
	v_sub_u32_e32 v1, v147, v1
	v_lshlrev_b32_e32 v148, 8, v1
	v_lshrrev_b32_e32 v1, 4, v0
	v_xor_b32_e32 v1, v1, v0
	s_add_u32 s38, s66, 0x4553700
	v_lshlrev_b32_e32 v1, 4, v1
	s_addc_u32 s39, s67, 0
	s_lshl_b32 s0, s23, 1
	v_add_u32_e32 v146, v2, v166
	v_mul_u32_u24_e32 v146, 0xc0, v146
	v_and_b32_e32 v128, 0x70, v1
	v_ashrrev_i32_e32 v1, 3, v0
	s_add_u32 s0, s66, s0
	v_add_u32_e32 v4, v146, v1
	s_addc_u32 s1, s67, 0
	v_ashrrev_i32_e32 v5, 31, v4
	v_lshl_add_u32 v6, v0, 4, 0
	s_add_u32 s40, s0, 0x1c4b700
	v_lshl_add_u64 v[2:3], s[38:39], 0, v[128:129]
	v_lshlrev_b64 v[4:5], 13, v[4:5]
	v_readfirstlane_b32 s0, v6
	v_add_u32_e32 v7, 0x200, v0
	v_lshl_add_u64 v[4:5], v[2:3], 0, v[4:5]
	s_mov_b32 m0, s0
	v_ashrrev_i32_e32 v8, 3, v7
	global_load_lds_dwordx4 v[4:5], off
	v_add_u32_e32 v4, v146, v8
	v_ashrrev_i32_e32 v5, 31, v4
	v_lshl_add_u32 v7, v7, 4, 0
	v_lshlrev_b64 v[4:5], 13, v[4:5]
	v_readfirstlane_b32 s0, v7
	v_add_u32_e32 v9, 0x400, v0
	v_lshl_add_u64 v[4:5], v[2:3], 0, v[4:5]
	s_mov_b32 m0, s0
	v_ashrrev_i32_e32 v10, 3, v9
	global_load_lds_dwordx4 v[4:5], off
	v_add_u32_e32 v4, v146, v10
	v_ashrrev_i32_e32 v5, 31, v4
	v_lshl_add_u32 v9, v9, 4, 0
	v_lshlrev_b64 v[4:5], 13, v[4:5]
	v_readfirstlane_b32 s0, v9
	v_add_u32_e32 v11, 0x600, v0
	v_lshl_add_u64 v[4:5], v[2:3], 0, v[4:5]
	s_mov_b32 m0, s0
	v_ashrrev_i32_e32 v12, 3, v11
	global_load_lds_dwordx4 v[4:5], off
	v_add_u32_e32 v4, v146, v12
	v_ashrrev_i32_e32 v5, 31, v4
	v_lshlrev_b64 v[4:5], 13, v[4:5]
	v_lshl_add_u32 v11, v11, 4, 0
	v_lshl_add_u64 v[2:3], v[2:3], 0, v[4:5]
	v_readfirstlane_b32 s0, v11
	v_add_u32_e32 v4, v148, v1
	s_addc_u32 s41, s1, 0
	s_mov_b32 m0, s0
	v_ashrrev_i32_e32 v5, 31, v4
	v_add_u32_e32 v1, 0x8000, v6
	v_lshl_add_u64 v[2:3], s[40:41], 0, v[128:129]
	v_lshlrev_b64 v[4:5], 13, v[4:5]
	v_readfirstlane_b32 s0, v1
	v_lshl_add_u64 v[4:5], v[2:3], 0, v[4:5]
	s_mov_b32 m0, s0
	v_add_u32_e32 v1, 0x8000, v7
	global_load_lds_dwordx4 v[4:5], off
	v_lshl_add_u64 v[14:15], v[4:5], 0, 64
	v_lshl_add_u64 v[14:15], v[14:15], 0, 64
	s_add_u32 m0, m0, 0x8000
	s_nop 0
	global_load_lds_dwordx4 v[14:15], off
	v_add_u32_e32 v4, v148, v8
	v_ashrrev_i32_e32 v5, 31, v4
	v_lshlrev_b64 v[4:5], 13, v[4:5]
	v_readfirstlane_b32 s0, v1
	v_lshl_add_u64 v[4:5], v[2:3], 0, v[4:5]
	s_mov_b32 m0, s0
	v_add_u32_e32 v1, 0x8000, v9
	global_load_lds_dwordx4 v[4:5], off
	v_lshl_add_u64 v[14:15], v[4:5], 0, 64
	v_lshl_add_u64 v[14:15], v[14:15], 0, 64
	s_add_u32 m0, m0, 0x8000
	s_nop 0
	global_load_lds_dwordx4 v[14:15], off
	v_add_u32_e32 v4, v148, v10
	v_ashrrev_i32_e32 v5, 31, v4
	v_lshlrev_b64 v[4:5], 13, v[4:5]
	v_readfirstlane_b32 s0, v1
	v_lshl_add_u64 v[4:5], v[2:3], 0, v[4:5]
	s_mov_b32 m0, s0
	v_add_u32_e32 v1, 0x8000, v11
	global_load_lds_dwordx4 v[4:5], off
	v_lshl_add_u64 v[14:15], v[4:5], 0, 64
	v_lshl_add_u64 v[14:15], v[14:15], 0, 64
	s_add_u32 m0, m0, 0x8000
	s_nop 0
	global_load_lds_dwordx4 v[14:15], off
	v_add_u32_e32 v4, v148, v12
	v_ashrrev_i32_e32 v5, 31, v4
	v_lshlrev_b64 v[4:5], 13, v[4:5]
	v_readfirstlane_b32 s0, v1
	v_lshl_add_u64 v[2:3], v[2:3], 0, v[4:5]
	s_mov_b32 m0, s0
	s_load_dword s0, s[24:25], 0x0
	global_load_lds_dwordx4 v[2:3], off
	v_lshl_add_u64 v[14:15], v[2:3], 0, 64
	v_lshl_add_u64 v[14:15], v[14:15], 0, 64
	s_add_u32 m0, m0, 0x8000
	s_nop 0
	global_load_lds_dwordx4 v[14:15], off
	v_ashrrev_i32_e32 v1, 1, v0
	v_and_b32_e32 v167, 0xdf, v0
	v_lshrrev_b32_e32 v0, 3, v0
	s_waitcnt lgkmcnt(0)
	s_lshr_b32 s8, s0, 3
	v_and_b32_e32 v0, 4, v0
	s_movk_i32 s0, 0xff80
	v_lshrrev_b32_e32 v1, 8, v224
	v_mul_u32_u24_e32 v1, 0x60, v1
	v_add_u32_e32 v168, v1, v0
	v_readlane_b32 s0, v253, 57
	s_add_u32 s42, s0, s74
	v_readlane_b32 s0, v253, 58
	s_addc_u32 s43, s0, s75
	v_readlane_b32 s0, v254, 59
	s_add_u32 s44, s0, s74
	v_readlane_b32 s0, v254, 60
	s_addc_u32 s45, s0, s75
	s_add_u32 s44, s44, 0x80
	s_addc_u32 s45, s45, 0
	s_mov_b32 s9, 0
	s_mov_b64 s[46:47], 0
	s_branch .LBB0_225

.LBB0_225:
	v_mov_b32_e32 v246, 0
	v_mov_b32_e32 v247, 0x8000
	v_mov_b32_e32 v248, 0x10000
	v_mov_b32_e32 v32, v224
	v_mov_b32_e32 v170, v146
	v_and_b32_e32 v0, 31, v32
	v_lshrrev_b32_e32 v1, 1, v32
	v_lshrrev_b32_e32 v1, 8, v32
	v_mul_u32_u24_e32 v1, 0x60, v1
	v_add_u32_e32 v0, v1, v0
	v_lshlrev_b32_e32 v182, 7, v0
	v_lshlrev_b32_e32 v0, 7, v32
	v_and_b32_e32 v183, 0x6f80, v0
	v_lshrrev_b32_e32 v0, 5, v32
	v_bfe_u32 v2, v32, 1, 3
	v_bfe_u32 v1, v32, 5, 1
	v_bitop3_b32 v0, v0, v2, 1 bitop3:0x6c
	v_lshlrev_b32_e32 v184, 4, v0
	v_bitop3_b32 v0, v1, v2, 2 bitop3:0x36
	v_lshlrev_b32_e32 v181, 4, v0
	v_bitop3_b32 v0, v1, v2, 4 bitop3:0x36
	v_ashrrev_i32_e32 v188, 3, v32
	v_add_u32_e32 v3, 0x200, v32
	v_add_u32_e32 v4, 0x400, v32
	v_add_u32_e32 v5, 0x600, v32
	v_lshlrev_b32_e32 v172, 4, v0
	v_bitop3_b32 v0, v1, v2, 6 bitop3:0x36
	v_mov_b32_e32 v169, v148
	s_movk_i32 s0, 0xff
	v_lshrrev_b32_e32 v33, 4, v32
	v_ashrrev_i32_e32 v187, 3, v3
	v_ashrrev_i32_e32 v186, 3, v4
	v_ashrrev_i32_e32 v185, 3, v5
	v_lshrrev_b32_e32 v176, 3, v32
	v_lshrrev_b32_e32 v175, 3, v3
	v_lshrrev_b32_e32 v174, 3, v4
	v_lshrrev_b32_e32 v173, 3, v5
	v_lshlrev_b32_e32 v171, 4, v0
	v_add_u32_e32 v0, v188, v170
	v_cmp_gt_i32_e32 vcc, s73, v32
	v_cmp_lt_i32_e64 s[0:1], s0, v32
	v_xor_b32_e32 v132, v33, v32
	v_lshlrev_b32_e32 v180, 4, v32
	v_lshlrev_b32_e32 v178, 4, v4
	v_ashrrev_i32_e32 v1, 31, v0
	v_add_u32_e32 v2, v187, v170
	v_add_u32_e32 v4, v186, v170
	v_add_u32_e32 v6, v185, v170
	v_add_u32_e32 v8, v176, v170
	v_add_u32_e32 v10, v175, v170
	v_add_u32_e32 v12, v174, v170
	v_add_u32_e32 v14, v173, v170
	v_add_u32_e32 v16, v188, v169
	v_add_u32_e32 v18, v187, v169
	v_add_u32_e32 v20, v186, v169
	v_add_u32_e32 v22, v185, v169
	v_add_u32_e32 v24, v176, v169
	v_add_u32_e32 v26, v175, v169
	v_add_u32_e32 v28, v174, v169
	v_add_u32_e32 v30, v173, v169
	v_bitop3_b32 v32, v33, 7, v32 bitop3:0x48
	v_lshlrev_b32_e32 v179, 4, v3
	v_lshlrev_b32_e32 v177, 4, v5
	v_ashrrev_i32_e32 v3, 31, v2
	v_ashrrev_i32_e32 v5, 31, v4
	v_ashrrev_i32_e32 v7, 31, v6
	v_ashrrev_i32_e32 v9, 31, v8
	v_ashrrev_i32_e32 v11, 31, v10
	v_ashrrev_i32_e32 v13, 31, v12
	v_ashrrev_i32_e32 v15, 31, v14
	v_lshlrev_b64 v[0:1], 13, v[0:1]
	v_ashrrev_i32_e32 v17, 31, v16
	v_ashrrev_i32_e32 v19, 31, v18
	v_ashrrev_i32_e32 v21, 31, v20
	v_ashrrev_i32_e32 v23, 31, v22
	v_ashrrev_i32_e32 v25, 31, v24
	v_ashrrev_i32_e32 v27, 31, v26
	v_ashrrev_i32_e32 v29, 31, v28
	v_ashrrev_i32_e32 v31, 31, v30
	v_lshlrev_b32_e32 v32, 4, v32
	s_waitcnt vmcnt(0)
	v_lshlrev_b64 v[2:3], 13, v[2:3]
	v_lshlrev_b64 v[4:5], 13, v[4:5]
	v_lshlrev_b64 v[6:7], 13, v[6:7]
	v_lshlrev_b64 v[8:9], 13, v[8:9]
	v_lshlrev_b64 v[10:11], 13, v[10:11]
	v_lshlrev_b64 v[12:13], 13, v[12:13]
	v_lshlrev_b64 v[14:15], 13, v[14:15]
	v_lshlrev_b64 v[16:17], 13, v[16:17]
	v_lshlrev_b64 v[18:19], 13, v[18:19]
	v_lshlrev_b64 v[20:21], 13, v[20:21]
	v_lshlrev_b64 v[22:23], 13, v[22:23]
	v_lshlrev_b64 v[24:25], 13, v[24:25]
	v_lshlrev_b64 v[26:27], 13, v[26:27]
	v_lshlrev_b64 v[28:29], 13, v[28:29]
	v_lshlrev_b64 v[30:31], 13, v[30:31]
	v_or_b32_e32 v0, v0, v32
	v_lshl_add_u64 v[134:135], s[42:43], 0, v[0:1]
	v_or_b32_e32 v2, v2, v32
	v_or_b32_e32 v4, v4, v32
	v_or_b32_e32 v6, v6, v32
	v_or_b32_e32 v16, v16, v32
	v_or_b32_e32 v18, v18, v32
	v_or_b32_e32 v20, v20, v32
	v_or_b32_e32 v22, v22, v32
	v_or_b32_e32 v8, v8, v32
	v_or_b32_e32 v10, v10, v32
	v_or_b32_e32 v12, v12, v32
	v_or_b32_e32 v14, v14, v32
	v_or_b32_e32 v24, v24, v32
	v_or_b32_e32 v26, v26, v32
	v_or_b32_e32 v28, v28, v32
	v_or_b32_e32 v30, v30, v32
	v_mov_b32_e32 v0, 0
	v_mov_b32_e32 v128, v147
	v_lshl_add_u64 v[136:137], s[42:43], 0, v[2:3]
	v_lshl_add_u64 v[138:139], s[42:43], 0, v[4:5]
	v_lshl_add_u64 v[140:141], s[42:43], 0, v[6:7]
	v_lshl_add_u64 v[142:143], s[44:45], 0, v[16:17]
	v_lshl_add_u64 v[144:145], s[44:45], 0, v[18:19]
	v_lshl_add_u64 v[146:147], s[44:45], 0, v[20:21]
	v_lshl_add_u64 v[148:149], s[44:45], 0, v[22:23]
	v_lshl_add_u64 v[150:151], s[42:43], 0, v[8:9]
	v_lshl_add_u64 v[152:153], s[42:43], 0, v[10:11]
	v_lshl_add_u64 v[154:155], s[42:43], 0, v[12:13]
	v_lshl_add_u64 v[156:157], s[42:43], 0, v[14:15]
	v_lshl_add_u64 v[158:159], s[44:45], 0, v[24:25]
	v_lshl_add_u64 v[160:161], s[44:45], 0, v[26:27]
	v_lshl_add_u64 v[162:163], s[44:45], 0, v[28:29]
	v_lshl_add_u64 v[164:165], s[44:45], 0, v[30:31]
	s_mov_b64 s[4:5], 0
	v_mov_b32_e32 v1, v0
	v_mov_b32_e32 v2, v0
	v_mov_b32_e32 v3, v0
	v_mov_b32_e32 v4, v0
	v_mov_b32_e32 v5, v0
	v_mov_b32_e32 v6, v0
	v_mov_b32_e32 v7, v0
	v_mov_b32_e32 v8, v0
	v_mov_b32_e32 v9, v0
	v_mov_b32_e32 v10, v0
	v_mov_b32_e32 v11, v0
	v_mov_b32_e32 v12, v0
	v_mov_b32_e32 v13, v0
	v_mov_b32_e32 v14, v0
	v_mov_b32_e32 v15, v0
	v_mov_b32_e32 v16, v0
	v_mov_b32_e32 v17, v0
	v_mov_b32_e32 v18, v0
	v_mov_b32_e32 v19, v0
	v_mov_b32_e32 v20, v0
	v_mov_b32_e32 v21, v0
	v_mov_b32_e32 v22, v0
	v_mov_b32_e32 v23, v0
	v_mov_b32_e32 v24, v0
	v_mov_b32_e32 v25, v0
	v_mov_b32_e32 v26, v0
	v_mov_b32_e32 v27, v0
	v_mov_b32_e32 v28, v0
	v_mov_b32_e32 v29, v0
	v_mov_b32_e32 v30, v0
	v_mov_b32_e32 v31, v0
	v_mov_b32_e32 v32, v0
	v_mov_b32_e32 v33, v0
	v_mov_b32_e32 v34, v0
	v_mov_b32_e32 v35, v0
	v_mov_b32_e32 v36, v0
	v_mov_b32_e32 v37, v0
	v_mov_b32_e32 v38, v0
	v_mov_b32_e32 v39, v0
	v_mov_b32_e32 v40, v0
	v_mov_b32_e32 v41, v0
	v_mov_b32_e32 v42, v0
	v_mov_b32_e32 v43, v0
	v_mov_b32_e32 v44, v0
	v_mov_b32_e32 v45, v0
	v_mov_b32_e32 v46, v0
	v_mov_b32_e32 v47, v0
	v_mov_b32_e32 v48, v0
	v_mov_b32_e32 v49, v0
	v_mov_b32_e32 v50, v0
	v_mov_b32_e32 v51, v0
	v_mov_b32_e32 v52, v0
	v_mov_b32_e32 v53, v0
	v_mov_b32_e32 v54, v0
	v_mov_b32_e32 v55, v0
	v_mov_b32_e32 v56, v0
	v_mov_b32_e32 v57, v0
	v_mov_b32_e32 v58, v0
	v_mov_b32_e32 v59, v0
	v_mov_b32_e32 v60, v0
	v_mov_b32_e32 v61, v0
	v_mov_b32_e32 v62, v0
	v_mov_b32_e32 v63, v0
	v_mov_b32_e32 v64, v0
	v_mov_b32_e32 v65, v0
	v_mov_b32_e32 v66, v0
	v_mov_b32_e32 v67, v0
	v_mov_b32_e32 v68, v0
	v_mov_b32_e32 v69, v0
	v_mov_b32_e32 v70, v0
	v_mov_b32_e32 v71, v0
	v_mov_b32_e32 v72, v0
	v_mov_b32_e32 v73, v0
	v_mov_b32_e32 v74, v0
	v_mov_b32_e32 v75, v0
	v_mov_b32_e32 v76, v0
	v_mov_b32_e32 v77, v0
	v_mov_b32_e32 v78, v0
	v_mov_b32_e32 v79, v0
	v_mov_b32_e32 v80, v0
	v_mov_b32_e32 v81, v0
	v_mov_b32_e32 v82, v0
	v_mov_b32_e32 v83, v0
	v_mov_b32_e32 v84, v0
	v_mov_b32_e32 v85, v0
	v_mov_b32_e32 v86, v0
	v_mov_b32_e32 v87, v0
	v_mov_b32_e32 v88, v0
	v_mov_b32_e32 v89, v0
	v_mov_b32_e32 v90, v0
	v_mov_b32_e32 v91, v0
	v_mov_b32_e32 v92, v0
	v_mov_b32_e32 v93, v0
	v_mov_b32_e32 v94, v0
	v_mov_b32_e32 v95, v0
	v_mov_b32_e32 v96, v0
	v_mov_b32_e32 v97, v0
	v_mov_b32_e32 v98, v0
	v_mov_b32_e32 v99, v0
	v_mov_b32_e32 v100, v0
	v_mov_b32_e32 v101, v0
	v_mov_b32_e32 v102, v0
	v_mov_b32_e32 v103, v0
	v_mov_b32_e32 v104, v0
	v_mov_b32_e32 v105, v0
	v_mov_b32_e32 v106, v0
	v_mov_b32_e32 v107, v0
	v_mov_b32_e32 v108, v0
	v_mov_b32_e32 v109, v0
	v_mov_b32_e32 v110, v0
	v_mov_b32_e32 v111, v0
	v_mov_b32_e32 v112, v0
	v_mov_b32_e32 v113, v0
	v_mov_b32_e32 v114, v0
	v_mov_b32_e32 v115, v0
	v_mov_b32_e32 v116, v0
	v_mov_b32_e32 v117, v0
	v_mov_b32_e32 v118, v0
	v_mov_b32_e32 v119, v0
	v_mov_b32_e32 v120, v0
	v_mov_b32_e32 v121, v0
	v_mov_b32_e32 v122, v0
	v_mov_b32_e32 v123, v0
	v_mov_b32_e32 v124, v0
	v_mov_b32_e32 v125, v0
	v_mov_b32_e32 v126, v0
	v_mov_b32_e32 v127, v0
	s_waitcnt vmcnt(0)
	s_barrier
	s_mul_i32 s13, s9, 0x22000
	s_and_saveexec_b64 s[6:7], vcc
	s_cbranch_execz .LBB0_228
	s_branch .LBB0_227
.LBB0_226:
	s_mov_b32 s9, s6
	s_mul_i32 s13, s9, 0x22000
	s_and_saveexec_b64 s[6:7], vcc
	s_cbranch_execz .LBB0_228
.LBB0_227:
	s_xor_b32 s14, s13, 0x22000
	v_add_u32_e32 v133, s14, v180
	v_lshl_add_u64 v[130:131], v[134:135], 0, s[4:5]
	v_readfirstlane_b32 s15, v133
	s_nop 0
	s_mov_b32 m0, s15
	s_nop 0
	global_load_lds_dwordx4 v[130:131], off
	v_add_u32_e32 v133, s14, v179
	v_lshl_add_u64 v[130:131], v[136:137], 0, s[4:5]
	v_readfirstlane_b32 s15, v133
	s_nop 0
	s_mov_b32 m0, s15
	s_nop 0
	global_load_lds_dwordx4 v[130:131], off
	v_add_u32_e32 v133, s14, v178
	v_lshl_add_u64 v[130:131], v[138:139], 0, s[4:5]
	v_readfirstlane_b32 s15, v133
	s_nop 0
	s_mov_b32 m0, s15
	s_nop 0
	global_load_lds_dwordx4 v[130:131], off
	v_add_u32_e32 v249, 0x8000, v248
	v_add_u32_e32 v133, v249, v180
	v_lshl_add_u64 v[130:131], v[142:143], 0, s[4:5]
	v_readfirstlane_b32 s15, v133
	s_nop 0
	s_mov_b32 m0, s15
	s_nop 0
	global_load_lds_dwordx4 v[130:131], off
	v_add_u32_e32 v133, v249, v179
	v_lshl_add_u64 v[130:131], v[144:145], 0, s[4:5]
	v_readfirstlane_b32 s15, v133
	s_nop 0
	s_mov_b32 m0, s15
	s_nop 0
	global_load_lds_dwordx4 v[130:131], off
	v_add_u32_e32 v133, v249, v178
	v_lshl_add_u64 v[130:131], v[146:147], 0, s[4:5]
	v_readfirstlane_b32 s15, v133
	s_nop 0
	s_mov_b32 m0, s15
	s_nop 0
	global_load_lds_dwordx4 v[130:131], off
	v_add_u32_e32 v133, v249, v177
	v_lshl_add_u64 v[130:131], v[148:149], 0, s[4:5]
	v_readfirstlane_b32 s15, v133
	s_nop 0
	s_mov_b32 m0, s15
	s_nop 0
	global_load_lds_dwordx4 v[130:131], off
.LBB0_228:
	s_or_b64 exec, exec, s[6:7]
	s_add_i32 s6, s13, 0
	v_add_u32_e32 v131, s6, v182
	v_add_u32_e32 v133, v131, v184
	v_add_u32_e32 v130, v246, v183
	ds_read_b128 v[190:193], v133
	ds_read_b128 v[194:197], v133 offset:4096
	ds_read_b128 v[198:201], v133 offset:8192
	v_add_u32_e32 v133, v130, v184
	ds_read_b128 v[206:209], v133 offset:32768
	ds_read_b128 v[210:213], v133 offset:36864
	s_setprio 1
	s_waitcnt lgkmcnt(0)
	v_mfma_f32_32x32x16_bf16 v[112:127], v[190:193], v[206:209], v[112:127]
	v_mfma_f32_32x32x16_bf16 v[96:111], v[190:193], v[210:213], v[96:111]
	v_mfma_f32_32x32x16_bf16 v[80:95], v[194:197], v[206:209], v[80:95]
	v_mfma_f32_32x32x16_bf16 v[64:79], v[194:197], v[210:213], v[64:79]
	v_mfma_f32_32x32x16_bf16 v[48:63], v[198:201], v[206:209], v[48:63]
	v_mfma_f32_32x32x16_bf16 v[32:47], v[198:201], v[210:213], v[32:47]
	s_setprio 0
	v_add_u32_e32 v133, v131, v181
	ds_read_b128 v[190:193], v133
	ds_read_b128 v[194:197], v133 offset:4096
	ds_read_b128 v[198:201], v133 offset:8192
	v_add_u32_e32 v133, v130, v181
	ds_read_b128 v[206:209], v133 offset:32768
	ds_read_b128 v[210:213], v133 offset:36864
	s_setprio 1
	s_waitcnt lgkmcnt(0)
	v_mfma_f32_32x32x16_bf16 v[112:127], v[190:193], v[206:209], v[112:127]
	v_mfma_f32_32x32x16_bf16 v[96:111], v[190:193], v[210:213], v[96:111]
	v_mfma_f32_32x32x16_bf16 v[80:95], v[194:197], v[206:209], v[80:95]
	v_mfma_f32_32x32x16_bf16 v[64:79], v[194:197], v[210:213], v[64:79]
	v_mfma_f32_32x32x16_bf16 v[48:63], v[198:201], v[206:209], v[48:63]
	v_mfma_f32_32x32x16_bf16 v[32:47], v[198:201], v[210:213], v[32:47]
	s_setprio 0
	s_and_saveexec_b64 s[6:7], s[0:1]
	s_cbranch_execz .LBB0_230
	s_xor_b32 s14, s13, 0x22000
	v_add_u32_e32 v133, s14, v180
	v_lshl_add_u64 v[190:191], v[150:151], 0, s[4:5]
	v_readfirstlane_b32 s15, v133
	s_nop 0
	s_mov_b32 m0, s15
	s_nop 0
	global_load_lds_dwordx4 v[190:191], off
	v_add_u32_e32 v133, s14, v179
	v_lshl_add_u64 v[190:191], v[152:153], 0, s[4:5]
	v_readfirstlane_b32 s15, v133
	s_nop 0
	s_mov_b32 m0, s15
	s_nop 0
	global_load_lds_dwordx4 v[190:191], off
	v_add_u32_e32 v133, s14, v178
	v_lshl_add_u64 v[190:191], v[154:155], 0, s[4:5]
	v_readfirstlane_b32 s15, v133
	s_nop 0
	s_mov_b32 m0, s15
	s_nop 0
	global_load_lds_dwordx4 v[190:191], off
	v_add_u32_e32 v249, 0x8000, v248
	v_add_u32_e32 v133, v249, v180
	v_lshl_add_u64 v[190:191], v[158:159], 0, s[4:5]
	v_readfirstlane_b32 s15, v133
	s_nop 0
	s_mov_b32 m0, s15
	s_nop 0
	global_load_lds_dwordx4 v[190:191], off
	v_add_u32_e32 v133, v249, v179
	v_lshl_add_u64 v[190:191], v[160:161], 0, s[4:5]
	v_readfirstlane_b32 s15, v133
	s_nop 0
	s_mov_b32 m0, s15
	s_nop 0
	global_load_lds_dwordx4 v[190:191], off
	v_add_u32_e32 v133, v249, v178
	v_lshl_add_u64 v[190:191], v[162:163], 0, s[4:5]
	v_readfirstlane_b32 s15, v133
	s_nop 0
	s_mov_b32 m0, s15
	s_nop 0
	global_load_lds_dwordx4 v[190:191], off
	v_add_u32_e32 v133, v249, v177
	v_lshl_add_u64 v[190:191], v[164:165], 0, s[4:5]
	v_readfirstlane_b32 s15, v133
	s_nop 0
	s_mov_b32 m0, s15
	s_nop 0
	global_load_lds_dwordx4 v[190:191], off
.LBB0_230:
	s_or_b64 exec, exec, s[6:7]
	v_add_u32_e32 v133, v131, v172
	ds_read_b128 v[190:193], v133
	ds_read_b128 v[194:197], v133 offset:4096
	ds_read_b128 v[198:201], v133 offset:8192
	v_add_u32_e32 v133, v130, v172
	ds_read_b128 v[206:209], v133 offset:32768
	ds_read_b128 v[210:213], v133 offset:36864
	s_setprio 1
	s_waitcnt lgkmcnt(0)
	v_mfma_f32_32x32x16_bf16 v[112:127], v[190:193], v[206:209], v[112:127]
	v_mfma_f32_32x32x16_bf16 v[96:111], v[190:193], v[210:213], v[96:111]
	v_mfma_f32_32x32x16_bf16 v[80:95], v[194:197], v[206:209], v[80:95]
	v_mfma_f32_32x32x16_bf16 v[64:79], v[194:197], v[210:213], v[64:79]
	v_mfma_f32_32x32x16_bf16 v[48:63], v[198:201], v[206:209], v[48:63]
	v_mfma_f32_32x32x16_bf16 v[32:47], v[198:201], v[210:213], v[32:47]
	s_setprio 0
	v_add_u32_e32 v131, v131, v171
	ds_read_b128 v[190:193], v131
	ds_read_b128 v[194:197], v131 offset:4096
	ds_read_b128 v[198:201], v131 offset:8192
	v_add_u32_e32 v130, v130, v171
	ds_read_b128 v[206:209], v130 offset:32768
	ds_read_b128 v[210:213], v130 offset:36864
	s_setprio 1
	s_waitcnt lgkmcnt(0)
	v_mfma_f32_32x32x16_bf16 v[112:127], v[190:193], v[206:209], v[112:127]
	v_mfma_f32_32x32x16_bf16 v[96:111], v[190:193], v[210:213], v[96:111]
	v_mfma_f32_32x32x16_bf16 v[80:95], v[194:197], v[206:209], v[80:95]
	v_mfma_f32_32x32x16_bf16 v[64:79], v[194:197], v[210:213], v[64:79]
	v_mfma_f32_32x32x16_bf16 v[48:63], v[198:201], v[206:209], v[48:63]
	v_mfma_f32_32x32x16_bf16 v[32:47], v[198:201], v[210:213], v[32:47]
	s_setprio 0
	s_xor_b32 s6, s9, 1
	v_mov_b32_e32 v249, v246
	v_mov_b32_e32 v246, v247
	v_mov_b32_e32 v247, v248
	v_mov_b32_e32 v248, v249
	s_waitcnt vmcnt(4)
	s_add_u32 s4, s4, 0x80
	s_addc_u32 s5, s5, 0
	s_cmpk_lg_i32 s4, 0x1f80
	s_waitcnt vmcnt(4)
	s_barrier
	s_cbranch_scc1 .LBB0_226
	v_add_u32_e32 v147, s8, v128
	v_cmp_lt_i32_e64 s[0:1], 31, v147
	s_xor_b64 s[4:5], vcc, -1
	s_nor_b64 s[4:5], s[4:5], s[0:1]
	v_cndmask_b32_e64 v128, v147, v128, s[0:1]
	v_ashrrev_i32_e32 v130, 31, v128
	v_lshrrev_b32_e32 v130, 30, v130
	v_add_u32_e32 v130, v128, v130
	v_lshrrev_b32_e32 v131, 2, v130
	v_and_b32_e32 v130, 0xfffffc, v130
	v_sub_u32_e32 v130, v128, v130
	v_lshlrev_b32_e32 v128, 4, v132
	v_and_b32_e32 v128, 0x70, v128
	v_add_lshl_u32 v146, v131, v166, 8
	v_lshl_add_u64 v[136:137], s[38:39], 0, v[128:129]
	v_lshl_add_u64 v[134:135], s[40:41], 0, v[128:129]
	v_lshlrev_b32_e32 v148, 8, v130
	s_and_saveexec_b64 s[14:15], s[4:5]
	s_xor_b64 s[4:5], exec, s[14:15]
	s_cbranch_execz .LBB0_233
	s_lshl_b32 s7, s6, 16
	s_xor_b32 s13, s7, 0x10000
	v_add_u32_e32 v130, v146, v188
	s_add_i32 s13, s13, 0
	v_ashrrev_i32_e32 v131, 31, v130
	v_add_u32_e32 v132, v187, v146
	v_add_u32_e32 v128, s13, v180
	v_lshlrev_b64 v[130:131], 13, v[130:131]
	v_ashrrev_i32_e32 v133, 31, v132
	v_readfirstlane_b32 s14, v128
	v_add_u32_e32 v142, s13, v179
	v_lshl_add_u64 v[130:131], v[136:137], 0, v[130:131]
	v_lshlrev_b64 v[132:133], 13, v[132:133]
	s_mov_b32 m0, s14
	v_readfirstlane_b32 s14, v142
	v_lshl_add_u64 v[132:133], v[136:137], 0, v[132:133]
	v_add_u32_e32 v138, v186, v146
	global_load_lds_dwordx4 v[130:131], off
	s_mov_b32 m0, s14
	v_ashrrev_i32_e32 v139, 31, v138
	v_add_u32_e32 v140, v185, v146
	global_load_lds_dwordx4 v[132:133], off
	v_add_u32_e32 v132, s13, v178
	v_lshlrev_b64 v[138:139], 13, v[138:139]
	v_ashrrev_i32_e32 v141, 31, v140
	v_readfirstlane_b32 s14, v132
	v_add_u32_e32 v133, s13, v177
	v_add_u32_e32 v130, v148, v188
	v_lshl_add_u64 v[138:139], v[136:137], 0, v[138:139]
	v_lshlrev_b64 v[140:141], 13, v[140:141]
	s_mov_b32 m0, s14
	v_readfirstlane_b32 s13, v133
	v_ashrrev_i32_e32 v131, 31, v130
	v_add_u32_e32 v128, 0x8000, v128
	v_lshl_add_u64 v[140:141], v[136:137], 0, v[140:141]
	global_load_lds_dwordx4 v[138:139], off
	s_mov_b32 m0, s13
	v_lshlrev_b64 v[130:131], 13, v[130:131]
	v_readfirstlane_b32 s13, v128
	global_load_lds_dwordx4 v[140:141], off
	v_lshl_add_u64 v[130:131], v[134:135], 0, v[130:131]
	s_mov_b32 m0, s13
	v_add_u32_e32 v128, 0x8000, v142
	global_load_lds_dwordx4 v[130:131], off
	v_add_u32_e32 v130, v187, v148
	v_ashrrev_i32_e32 v131, 31, v130
	v_lshlrev_b64 v[130:131], 13, v[130:131]
	v_readfirstlane_b32 s13, v128
	v_lshl_add_u64 v[130:131], v[134:135], 0, v[130:131]
	s_mov_b32 m0, s13
	v_add_u32_e32 v128, 0x8000, v132
	global_load_lds_dwordx4 v[130:131], off
	v_add_u32_e32 v130, v186, v148
	v_ashrrev_i32_e32 v131, 31, v130
	v_lshlrev_b64 v[130:131], 13, v[130:131]
	v_readfirstlane_b32 s13, v128
	v_lshl_add_u64 v[130:131], v[134:135], 0, v[130:131]
	s_mov_b32 m0, s13
	v_add_u32_e32 v128, 0x8000, v133
	global_load_lds_dwordx4 v[130:131], off
	v_add_u32_e32 v130, v185, v148
	v_ashrrev_i32_e32 v131, 31, v130
	v_lshlrev_b64 v[130:131], 13, v[130:131]
	v_readfirstlane_b32 s13, v128
	v_lshl_add_u64 v[130:131], v[134:135], 0, v[130:131]
	s_mov_b32 m0, s13
	s_nop 0
	global_load_lds_dwordx4 v[130:131], off
.LBB0_233:
	s_or_saveexec_b64 s[4:5], s[4:5]
	v_mov_b32_e32 v131, s7
	s_xor_b64 exec, exec, s[4:5]
	s_mul_i32 s6, s6, 0x22000
	v_mov_b32_e32 v131, s6
	s_or_b64 exec, exec, s[4:5]
	v_add_u32_e32 v128, 0, v131
	v_add_u32_e32 v130, v128, v182
	v_add_u32_e32 v132, v130, v184
	v_add_u32_e32 v128, v246, v183
	ds_read_b128 v[138:141], v132
	ds_read_b128 v[142:145], v132 offset:4096
	ds_read_b128 v[150:153], v132 offset:8192
	v_add_u32_e32 v132, v128, v184
	ds_read_b128 v[158:161], v132 offset:32768
	ds_read_b128 v[162:165], v132 offset:36864
	s_and_b64 s[4:5], exec, s[0:1]
	s_or_b64 s[46:47], s[4:5], s[46:47]
	s_setprio 1
	s_waitcnt lgkmcnt(0)
	v_mfma_f32_32x32x16_bf16 v[112:127], v[138:141], v[158:161], v[112:127]
	v_mfma_f32_32x32x16_bf16 v[96:111], v[138:141], v[162:165], v[96:111]
	v_mfma_f32_32x32x16_bf16 v[80:95], v[142:145], v[158:161], v[80:95]
	v_mfma_f32_32x32x16_bf16 v[64:79], v[142:145], v[162:165], v[64:79]
	v_mfma_f32_32x32x16_bf16 v[48:63], v[150:153], v[158:161], v[48:63]
	v_mfma_f32_32x32x16_bf16 v[32:47], v[150:153], v[162:165], v[32:47]
	s_setprio 0
	v_add_u32_e32 v132, v130, v181
	ds_read_b128 v[138:141], v132
	ds_read_b128 v[142:145], v132 offset:4096
	ds_read_b128 v[150:153], v132 offset:8192
	v_add_u32_e32 v132, v128, v181
	ds_read_b128 v[158:161], v132 offset:32768
	ds_read_b128 v[162:165], v132 offset:36864
	s_setprio 1
	s_waitcnt lgkmcnt(0)
	v_mfma_f32_32x32x16_bf16 v[112:127], v[138:141], v[158:161], v[112:127]
	v_mfma_f32_32x32x16_bf16 v[96:111], v[138:141], v[162:165], v[96:111]
	v_mfma_f32_32x32x16_bf16 v[80:95], v[142:145], v[158:161], v[80:95]
	v_mfma_f32_32x32x16_bf16 v[64:79], v[142:145], v[162:165], v[64:79]
	v_mfma_f32_32x32x16_bf16 v[48:63], v[150:153], v[158:161], v[48:63]
	v_mfma_f32_32x32x16_bf16 v[32:47], v[150:153], v[162:165], v[32:47]
	s_setprio 0
	s_nor_b64 s[4:5], vcc, s[0:1]
	s_and_saveexec_b64 s[0:1], s[4:5]
	s_cbranch_execz .LBB0_224
	v_add_u32_e32 v132, v173, v146
	v_add_u32_e32 v138, v146, v176
	v_add_u32_e32 v140, v175, v146
	v_add_u32_e32 v142, v174, v146
	v_ashrrev_i32_e32 v133, 31, v132
	v_ashrrev_i32_e32 v139, 31, v138
	v_ashrrev_i32_e32 v141, 31, v140
	v_ashrrev_i32_e32 v143, 31, v142
	v_xor_b32_e32 v131, 0x10000, v131
	v_lshlrev_b64 v[132:133], 13, v[132:133]
	v_lshlrev_b64 v[138:139], 13, v[138:139]
	v_lshlrev_b64 v[140:141], 13, v[140:141]
	v_lshlrev_b64 v[142:143], 13, v[142:143]
	v_add_u32_e32 v131, 0, v131
	v_lshl_add_u64 v[132:133], v[136:137], 0, v[132:133]
	v_lshl_add_u64 v[138:139], v[136:137], 0, v[138:139]
	v_lshl_add_u64 v[140:141], v[136:137], 0, v[140:141]
	v_lshl_add_u64 v[136:137], v[136:137], 0, v[142:143]
	v_add_u32_e32 v142, v131, v180
	s_nop 0
	v_readfirstlane_b32 s4, v142
	s_mov_b32 m0, s4
	s_nop 0
	global_load_lds_dwordx4 v[138:139], off
	v_add_u32_e32 v138, v131, v179
	v_add_u32_e32 v139, v131, v178
	v_readfirstlane_b32 s4, v138
	s_mov_b32 m0, s4
	v_readfirstlane_b32 s4, v139
	v_add_u32_e32 v131, v131, v177
	global_load_lds_dwordx4 v[140:141], off
	s_mov_b32 m0, s4
	v_readfirstlane_b32 s4, v131
	global_load_lds_dwordx4 v[136:137], off
	s_mov_b32 m0, s4
	v_add_u32_e32 v136, 0x8000, v142
	global_load_lds_dwordx4 v[132:133], off
	v_add_u32_e32 v132, v148, v176
	v_ashrrev_i32_e32 v133, 31, v132
	v_lshlrev_b64 v[132:133], 13, v[132:133]
	v_readfirstlane_b32 s4, v136
	v_lshl_add_u64 v[132:133], v[134:135], 0, v[132:133]
	s_mov_b32 m0, s4
	v_add_u32_e32 v136, 0x8000, v138
	global_load_lds_dwordx4 v[132:133], off
	v_add_u32_e32 v132, v175, v148
	v_ashrrev_i32_e32 v133, 31, v132
	v_lshlrev_b64 v[132:133], 13, v[132:133]
	v_readfirstlane_b32 s4, v136
	v_lshl_add_u64 v[132:133], v[134:135], 0, v[132:133]
	s_mov_b32 m0, s4
	v_add_u32_e32 v136, 0x8000, v139
	global_load_lds_dwordx4 v[132:133], off
	v_add_u32_e32 v132, v174, v148
	v_ashrrev_i32_e32 v133, 31, v132
	v_lshlrev_b64 v[132:133], 13, v[132:133]
	v_readfirstlane_b32 s4, v136
	v_lshl_add_u64 v[132:133], v[134:135], 0, v[132:133]
	s_mov_b32 m0, s4
	v_add_u32_e32 v131, 0x8000, v131
	global_load_lds_dwordx4 v[132:133], off
	v_add_u32_e32 v132, v173, v148
	v_ashrrev_i32_e32 v133, 31, v132
	v_lshlrev_b64 v[132:133], 13, v[132:133]
	v_readfirstlane_b32 s4, v131
	v_lshl_add_u64 v[132:133], v[134:135], 0, v[132:133]
	s_mov_b32 m0, s4
	s_nop 0
	global_load_lds_dwordx4 v[132:133], off
	s_branch .LBB0_224

	.amdhsa_kernel _Z8fwd_mega1P
		.amdhsa_group_segment_fixed_size 28656
		.amdhsa_private_segment_fixed_size 0
		.amdhsa_kernarg_size 600
		.amdhsa_user_sgpr_count 2
		.amdhsa_user_sgpr_dispatch_ptr 0
		.amdhsa_user_sgpr_queue_ptr 0
		.amdhsa_user_sgpr_kernarg_segment_ptr 1
		.amdhsa_user_sgpr_dispatch_id 0
		.amdhsa_user_sgpr_kernarg_preload_length 0
		.amdhsa_user_sgpr_kernarg_preload_offset 0
		.amdhsa_user_sgpr_private_segment_size 0
		.amdhsa_uses_dynamic_stack 0
		.amdhsa_enable_private_segment 0
		.amdhsa_system_sgpr_workgroup_id_x 1
		.amdhsa_system_sgpr_workgroup_id_y 0
		.amdhsa_system_sgpr_workgroup_id_z 0
		.amdhsa_system_sgpr_workgroup_info 0
		.amdhsa_system_vgpr_workitem_id 2
		.amdhsa_next_free_vgpr 256
		.amdhsa_next_free_sgpr 100
		.amdhsa_accum_offset 256
		.amdhsa_reserve_vcc 1
		.amdhsa_float_round_mode_32 0
		.amdhsa_float_round_mode_16_64 0
		.amdhsa_float_denorm_mode_32 3
		.amdhsa_float_denorm_mode_16_64 3
		.amdhsa_dx10_clamp 1
		.amdhsa_ieee_mode 1
		.amdhsa_fp16_overflow 0
		.amdhsa_tg_split 0
		.amdhsa_exception_fp_ieee_invalid_op 0
		.amdhsa_exception_fp_denorm_src 0
		.amdhsa_exception_fp_ieee_div_zero 0
		.amdhsa_exception_fp_ieee_overflow 0
		.amdhsa_exception_fp_ieee_underflow 0
		.amdhsa_exception_fp_ieee_inexact 0
		.amdhsa_exception_int_div_zero 0
	.end_amdhsa_kernel

amdhsa.kernels:
  - .agpr_count:     0
    .args:
      - .offset:         0
        .size:           344
        .value_kind:     by_value
      - .offset:         344
        .size:           4
        .value_kind:     hidden_block_count_x
      - .offset:         348
        .size:           4
        .value_kind:     hidden_block_count_y
      - .offset:         352
        .size:           4
        .value_kind:     hidden_block_count_z
      - .offset:         356
        .size:           2
        .value_kind:     hidden_group_size_x
      - .offset:         358
        .size:           2
        .value_kind:     hidden_group_size_y
      - .offset:         360
        .size:           2
        .value_kind:     hidden_group_size_z
      - .offset:         362
        .size:           2
        .value_kind:     hidden_remainder_x
      - .offset:         364
        .size:           2
        .value_kind:     hidden_remainder_y
      - .offset:         366
        .size:           2
        .value_kind:     hidden_remainder_z
      - .offset:         384
        .size:           8
        .value_kind:     hidden_global_offset_x
      - .offset:         392
        .size:           8
        .value_kind:     hidden_global_offset_y
      - .offset:         400
        .size:           8
        .value_kind:     hidden_global_offset_z
      - .offset:         408
        .size:           2
        .value_kind:     hidden_grid_dims
      - .offset:         432
        .size:           8
        .value_kind:     hidden_multigrid_sync_arg
      - .offset:         464
        .size:           4
        .value_kind:     hidden_dynamic_lds_size
    .group_segment_fixed_size: 28656
    .kernarg_segment_align: 8
    .kernarg_segment_size: 600
    .language:       OpenCL C
    .language_version:
      - 2
      - 0
    .max_flat_workgroup_size: 512
    .name:           _Z8fwd_mega1P
    .private_segment_fixed_size: 0
    .sgpr_count:     106
    .sgpr_spill_count: 338
    .symbol:         _Z8fwd_mega1P.kd
    .uniform_work_group_size: 1
    .uses_dynamic_stack: false
    .vgpr_count:     256
    .vgpr_spill_count: 0
    .wavefront_size: 64
